# final LayerNorm phase: gamma/beta loaded once per wave into registers, the 12 per-chunk parameter loads become register moves and the per-chunk vmcnt(0) waits are gone (on top of v13)
# speedup vs baseline: 1.0244x; 1.0048x over previous
; #define OPAQUE_V(x) asm volatile("" : "+v"(x))
; __device__ __forceinline__ void phase_ln(KP p, int l) {
;     int tid_ = threadIdx.x; OPAQUE_V(tid_); const int tid = tid_, wid = tid >> 6, lane = tid & 63;
;     const float* lng = p->in[16] + l * DM; const float* lnb = p->in[17] + l * DM;
;     bf16_t* xb = (bf16_t*)(p->ws + WS_XB);
;     for (int row = blockIdx.x * 8 + wid; row < SEQ; row += gridDim.x * 8) {
;         float* xr = p->out + (size_t)row * DM + lane * 4;
;         f32x4 v[8]; float sm = 0.f;
; #pragma unroll
;         for (int j = 0; j < 8; ++j) { v[j] = *(const f32x4*)(xr + 256 * j); sm += (v[j][0] + v[j][1]) + (v[j][2] + v[j][3]); }
;         const float mean = wave_sum(sm) * (1.f / DM); float sq = 0.f;
; #pragma unroll
;         for (int j = 0; j < 8; ++j) { v[j] = v[j] - mean; sq += (v[j][0] * v[j][0] + v[j][1] * v[j][1]) + (v[j][2] * v[j][2] + v[j][3] * v[j][3]); }
;         const float rstd = rsqrtf(wave_sum(sq) * (1.f / DM) + LN_EPS);
; #pragma unroll
;         for (int j = 0; j < 8; ++j) { const int c = lane * 4 + 256 * j;
.LBB0_896:
	v_readlane_b32 s41, v241, 5
	s_cmp_le_i32 s41, s6
	v_readlane_b32 s22, v241, 2
	s_cselect_b64 s[14:15], -1, 0
	s_cmp_lt_i32 s6, s22
	s_cselect_b64 s[26:27], -1, 0
	s_and_b64 s[22:23], s[14:15], s[26:27]
	s_andn2_b64 vcc, exec, s[22:23]
	v_readlane_b32 s40, v240, 0
	s_cbranch_vccnz .LBB0_917
	v_mov_b32_e32 v0, v166
	v_readlane_b32 s6, v241, 63
	v_ashrrev_i32_e32 v2, 6, v0
	s_nop 0
	v_add_u32_e32 v34, s6, v2
	s_movk_i32 s6, 0x4000
	v_cmp_gt_i32_e32 vcc, s6, v34
	s_and_saveexec_b64 s[34:35], vcc
	s_cbranch_execz .LBB0_916
	v_and_b32_e32 v2, 64, v172
	v_add_u32_e32 v2, 64, v2
	v_xor_b32_e32 v3, 1, v172
	v_cmp_lt_i32_e32 vcc, v3, v2
	s_load_dwordx4 s[36:39], s[0:1], 0x80
	s_waitcnt lgkmcnt(0)
	s_add_u32 s28, s28, 0xc300000
	v_cndmask_b32_e32 v3, v172, v3, vcc
	v_lshlrev_b32_e32 v37, 2, v3
	v_xor_b32_e32 v3, 2, v172
	v_cmp_lt_i32_e32 vcc, v3, v2
	v_readlane_b32 s22, v240, 33
	s_addc_u32 s29, s29, 0
	v_cndmask_b32_e32 v3, v172, v3, vcc
	v_lshlrev_b32_e32 v72, 2, v3
	v_xor_b32_e32 v3, 4, v172
	v_cmp_lt_i32_e32 vcc, v3, v2
	v_readlane_b32 s23, v240, 34
	s_lshl_b32 s6, s22, 11
	v_cndmask_b32_e32 v3, v172, v3, vcc
	v_lshlrev_b32_e32 v73, 2, v3
	v_xor_b32_e32 v3, 8, v172
	v_cmp_lt_i32_e32 vcc, v3, v2
	s_lshl_b64 s[22:23], s[6:7], 2
	s_load_dwordx2 s[0:1], s[0:1], 0x90
	v_cndmask_b32_e32 v3, v172, v3, vcc
	v_lshlrev_b32_e32 v74, 2, v3
	v_xor_b32_e32 v3, 16, v172
	v_cmp_lt_i32_e32 vcc, v3, v2
	s_add_u32 s24, s38, s22
	v_lshlrev_b32_e32 v0, 2, v0
	v_cndmask_b32_e32 v3, v172, v3, vcc
	v_lshlrev_b32_e32 v75, 2, v3
	v_xor_b32_e32 v3, 32, v172
	s_addc_u32 s25, s39, s23
	v_and_b32_e32 v36, 0xfc, v0
	v_cmp_lt_i32_e32 vcc, v3, v2
	s_add_u32 s22, s36, s22
	v_lshlrev_b32_e32 v0, 2, v36
	v_cndmask_b32_e32 v2, v172, v3, vcc
	s_addc_u32 s23, s37, s23
	v_lshlrev_b32_e32 v76, 2, v2
	v_or_b32_e32 v2, 0x1000, v0
	v_mov_b32_e32 v3, v1
	v_lshl_add_u64 v[44:45], s[22:23], 0, v[2:3]
	v_lshl_add_u64 v[46:47], s[24:25], 0, v[2:3]
	v_or_b32_e32 v2, 0x1400, v0
	s_waitcnt lgkmcnt(0)
	v_lshl_add_u64 v[38:39], s[0:1], 0, v[0:1]
	v_lshl_add_u64 v[40:41], s[22:23], 0, v[0:1]
	v_lshl_add_u64 v[42:43], s[24:25], 0, v[0:1]
	v_lshl_add_u64 v[48:49], s[22:23], 0, v[2:3]
	v_lshl_add_u64 v[50:51], s[24:25], 0, v[2:3]
	v_or_b32_e32 v2, 0x1800, v0
	v_or_b32_e32 v0, 0x1c00, v0
	v_lshl_add_u64 v[52:53], s[22:23], 0, v[2:3]
	v_lshl_add_u64 v[54:55], s[24:25], 0, v[2:3]
	v_lshl_add_u64 v[56:57], s[22:23], 0, v[0:1]
	v_lshl_add_u64 v[58:59], s[24:25], 0, v[0:1]
	s_mov_b64 s[0:1], 0
	global_load_dwordx4 v[86:89], v[40:41], off
	global_load_dwordx4 v[90:93], v[40:41], off offset:1024
	global_load_dwordx4 v[94:97], v[40:41], off offset:2048
	global_load_dwordx4 v[98:101], v[40:41], off offset:3072
	global_load_dwordx4 v[102:105], v[44:45], off
	global_load_dwordx4 v[106:109], v[48:49], off
	global_load_dwordx4 v[110:113], v[52:53], off
	global_load_dwordx4 v[114:117], v[56:57], off
	global_load_dwordx4 v[118:121], v[42:43], off
	global_load_dwordx4 v[122:125], v[42:43], off offset:1024
	global_load_dwordx4 v[126:129], v[42:43], off offset:2048
	global_load_dwordx4 v[130:133], v[42:43], off offset:3072
	global_load_dwordx4 v[134:137], v[46:47], off
	global_load_dwordx4 v[174:177], v[50:51], off
	global_load_dwordx4 v[178:181], v[54:55], off
	global_load_dwordx4 v[182:185], v[58:59], off
	s_branch .LBB0_900

; __device__ __forceinline__ void phase_ln(KP p, int l) {
;     ...
;     for (int row = blockIdx.x * 8 + wid; row < SEQ; row += gridDim.x * 8) {
;         float* xr = p->out + (size_t)row * DM + lane * 4;
;         f32x4 v[8]; float sm = 0.f;
; #pragma unroll
;         for (int j = 0; j < 8; ++j) { v[j] = *(const f32x4*)(xr + 256 * j); sm += (v[j][0] + v[j][1]) + (v[j][2] + v[j][3]); }
;         const float mean = wave_sum(sm) * (1.f / DM); float sq = 0.f;
; #pragma unroll
;         for (int j = 0; j < 8; ++j) { v[j] = v[j] - mean; sq += (v[j][0] * v[j][0] + v[j][1] * v[j][1]) + (v[j][2] * v[j][2] + v[j][3] * v[j][3]); }
;         const float rstd = rsqrtf(wave_sum(sq) * (1.f / DM) + LN_EPS);
; #pragma unroll
;         for (int j = 0; j < 8; ++j) { const int c = lane * 4 + 256 * j;
;             const f32x4 y = v[j] * rstd * *(const f32x4*)(lng + c) + *(const f32x4*)(lnb + c);
;             *(f32x4*)(xr + 256 * j) = y;
.LBB0_900:
	v_ashrrev_i32_e32 v35, 31, v34
	v_lshlrev_b64 v[2:3], 13, v[34:35]
	v_lshl_add_u64 v[60:61], v[38:39], 0, v[2:3]
	global_load_dwordx4 v[30:33], v[60:61], off
	global_load_dwordx4 v[26:29], v[60:61], off offset:1024
	global_load_dwordx4 v[18:21], v[60:61], off offset:2048
	global_load_dwordx4 v[22:25], v[60:61], off offset:3072
	v_add_co_u32_e32 v62, vcc, s2, v60
	s_mov_b64 s[24:25], -1
	s_nop 0
	v_addc_co_u32_e32 v63, vcc, 0, v61, vcc
	global_load_dwordx4 v[10:13], v[62:63], off
	global_load_dwordx4 v[14:17], v[62:63], off offset:1024
	s_waitcnt vmcnt(0)
	v_mov_b32_e32 v2, v30
	v_mov_b32_e32 v3, v26
	v_mov_b32_e32 v4, v31
	v_mov_b32_e32 v5, v27
	v_pk_add_f32 v[2:3], v[2:3], v[4:5]
	v_mov_b32_e32 v4, v32
	v_mov_b32_e32 v5, v28
	v_mov_b32_e32 v6, v33
	v_mov_b32_e32 v7, v29
	v_pk_add_f32 v[4:5], v[4:5], v[6:7]
	v_mov_b32_e32 v6, v18
	v_pk_add_f32 v[2:3], v[2:3], v[4:5]
	v_mov_b32_e32 v4, v19
	v_mov_b32_e32 v5, v20
	v_mov_b32_e32 v7, v21
	v_pk_add_f32 v[4:5], v[4:5], v[6:7]
	v_add_f32_e32 v0, 0, v2
	v_pk_add_f32 v[4:5], v[4:5], v[4:5] op_sel:[0,1] op_sel_hi:[1,0]
	v_add_f32_e32 v2, v0, v3
	v_add_f32_e32 v6, v22, v23
	v_add_f32_e32 v8, v24, v25
	v_mov_b32_e32 v3, v10
	v_mov_b32_e32 v5, v11
	v_mov_b32_e32 v7, v12
	v_mov_b32_e32 v9, v13
	v_pk_add_f32 v[2:3], v[2:3], v[4:5]
	v_pk_add_f32 v[4:5], v[6:7], v[8:9]
	global_load_dwordx4 v[6:9], v[62:63], off offset:2048
	v_pk_add_f32 v[2:3], v[2:3], v[4:5]
	v_mov_b32_e32 v4, v14
	v_pk_add_f32 v[64:65], v[2:3], v[2:3] op_sel:[0,1] op_sel_hi:[1,0]
	v_mov_b32_e32 v2, v15
	v_mov_b32_e32 v3, v16
	v_mov_b32_e32 v5, v17
	v_pk_add_f32 v[2:3], v[2:3], v[4:5]
	s_nop 0
	v_pk_add_f32 v[66:67], v[2:3], v[2:3] op_sel:[0,1] op_sel_hi:[1,0]
	global_load_dwordx4 v[2:5], v[62:63], off offset:3072
	s_waitcnt vmcnt(1)
	v_add_f32_e32 v68, v6, v7
	v_add_f32_e32 v70, v8, v9
	s_waitcnt vmcnt(0)
	v_mov_b32_e32 v65, v2
	v_mov_b32_e32 v67, v3
	v_mov_b32_e32 v69, v4
	v_mov_b32_e32 v71, v5
	v_pk_add_f32 v[62:63], v[64:65], v[66:67]
	v_pk_add_f32 v[64:65], v[68:69], v[70:71]
	s_nop 0
	v_pk_add_f32 v[62:63], v[62:63], v[64:65]
	s_nop 0
	v_add_f32_e32 v0, v62, v63
	ds_bpermute_b32 v62, v37, v0
	s_waitcnt lgkmcnt(0)
	v_add_f32_e32 v0, v0, v62
	ds_bpermute_b32 v62, v72, v0
	s_waitcnt lgkmcnt(0)
	v_add_f32_e32 v0, v0, v62
	ds_bpermute_b32 v62, v73, v0
	s_waitcnt lgkmcnt(0)
	v_add_f32_e32 v0, v0, v62
	ds_bpermute_b32 v62, v74, v0
	s_waitcnt lgkmcnt(0)
	v_add_f32_e32 v0, v0, v62
	ds_bpermute_b32 v62, v75, v0
	s_waitcnt lgkmcnt(0)
	v_add_f32_e32 v0, v0, v62
	ds_bpermute_b32 v62, v76, v0
	s_waitcnt lgkmcnt(0)
	v_add_f32_e32 v77, v0, v62
	v_fmamk_f32 v31, v77, 0xba000000, v31
	v_fmamk_f32 v27, v77, 0xba000000, v27
	v_fmamk_f32 v79, v77, 0xba000000, v33
	v_fmamk_f32 v78, v77, 0xba000000, v32
	v_fmac_f32_e32 v30, 0xba000000, v77
	v_fmac_f32_e32 v26, 0xba000000, v77
	v_mov_b32_e32 v32, v31
	v_mov_b32_e32 v33, v27
	v_fmamk_f32 v69, v77, 0xba000000, v29
	v_fmamk_f32 v71, v77, 0xba000000, v28
	v_mov_b32_e32 v28, v30
	v_mov_b32_e32 v29, v26
	v_pk_mul_f32 v[32:33], v[32:33], v[32:33]
	v_mov_b32_e32 v68, v79
	v_pk_fma_f32 v[28:29], v[28:29], v[28:29], v[32:33]
	v_mov_b32_e32 v70, v78
	v_pk_mul_f32 v[32:33], v[68:69], v[68:69]
	v_fmamk_f32 v67, v77, 0xba000000, v21
	v_pk_fma_f32 v[32:33], v[70:71], v[70:71], v[32:33]
	v_fmamk_f32 v66, v77, 0xba000000, v20
	v_fmamk_f32 v19, v77, 0xba000000, v19
	v_fmac_f32_e32 v18, 0xba000000, v77
	v_pk_add_f32 v[28:29], v[28:29], v[32:33]
	v_pk_mul_f32 v[20:21], v[66:67], v[66:67]
	v_pk_mul_f32 v[32:33], v[18:19], v[18:19]
	v_fmac_f32_e32 v22, 0xba000000, v77
	v_pk_mov_b32 v[62:63], v[32:33], v[20:21] op_sel:[1,0]
	v_mov_b32_e32 v33, v21
	v_fmamk_f32 v64, v77, 0xba000000, v24
	v_fmamk_f32 v23, v77, 0xba000000, v23
	v_mul_f32_e32 v0, v22, v22
	v_pk_add_f32 v[20:21], v[62:63], v[32:33]
	v_fmamk_f32 v65, v77, 0xba000000, v25
	v_pk_fma_f32 v[24:25], v[22:23], v[22:23], v[0:1] op_sel_hi:[1,1,0]
	v_mul_f32_e32 v0, v64, v64
	v_pk_add_f32 v[28:29], v[28:29], v[28:29] op_sel_hi:[0,1]
	v_pk_add_f32 v[20:21], v[20:21], v[20:21] op_sel_hi:[0,1]
	v_pk_fma_f32 v[32:33], v[64:65], v[64:65], v[0:1] op_sel_hi:[1,1,0]
	v_fmamk_f32 v63, v77, 0xba000000, v13
	v_fmamk_f32 v62, v77, 0xba000000, v12
	v_fmamk_f32 v11, v77, 0xba000000, v11
	v_fmac_f32_e32 v10, 0xba000000, v77
	v_mul_f32_e32 v24, v10, v10
	v_mul_f32_e32 v32, v11, v11
	v_mul_f32_e32 v20, v62, v62
	v_mul_f32_e32 v28, v63, v63
	v_pk_add_f32 v[12:13], v[24:25], v[32:33]
	v_pk_add_f32 v[20:21], v[20:21], v[28:29]
	v_fmamk_f32 v33, v77, 0xba000000, v17
	v_pk_add_f32 v[12:13], v[12:13], v[20:21]
	v_fmamk_f32 v32, v77, 0xba000000, v16
	v_fmamk_f32 v15, v77, 0xba000000, v15
	v_fmac_f32_e32 v14, 0xba000000, v77
	v_pk_add_f32 v[20:21], v[12:13], v[12:13] op_sel_hi:[0,1]
	v_pk_mul_f32 v[12:13], v[32:33], v[32:33]
	v_pk_mul_f32 v[16:17], v[14:15], v[14:15]
	v_fmac_f32_e32 v6, 0xba000000, v77
	v_pk_mov_b32 v[24:25], v[16:17], v[12:13] op_sel:[1,0]
	v_mov_b32_e32 v17, v13
	v_pk_add_f32 v[12:13], v[24:25], v[16:17]
	v_fmamk_f32 v24, v77, 0xba000000, v8
	v_fmamk_f32 v7, v77, 0xba000000, v7
	v_mul_f32_e32 v0, v6, v6
	v_fmamk_f32 v25, v77, 0xba000000, v9
	v_pk_fma_f32 v[8:9], v[6:7], v[6:7], v[0:1] op_sel_hi:[1,1,0]
	v_mul_f32_e32 v0, v24, v24
	v_pk_add_f32 v[16:17], v[12:13], v[12:13] op_sel_hi:[0,1]
	v_pk_fma_f32 v[28:29], v[24:25], v[24:25], v[0:1] op_sel_hi:[1,1,0]
	v_fmamk_f32 v13, v77, 0xba000000, v5
	v_fmamk_f32 v12, v77, 0xba000000, v4
	v_fmamk_f32 v3, v77, 0xba000000, v3
	v_fmac_f32_e32 v2, 0xba000000, v77
	v_mul_f32_e32 v8, v2, v2
	v_mul_f32_e32 v28, v3, v3
	v_mul_f32_e32 v16, v12, v12
	v_mul_f32_e32 v20, v13, v13
	v_pk_add_f32 v[4:5], v[8:9], v[28:29]
	v_pk_add_f32 v[8:9], v[16:17], v[20:21]
	s_nop 0
	v_pk_add_f32 v[4:5], v[4:5], v[8:9]
	s_nop 0
	v_add_f32_e32 v0, v4, v5
	ds_bpermute_b32 v4, v37, v0
	s_waitcnt lgkmcnt(0)
	v_add_f32_e32 v0, v0, v4
	ds_bpermute_b32 v4, v72, v0
	s_waitcnt lgkmcnt(0)
	v_add_f32_e32 v0, v0, v4
	ds_bpermute_b32 v4, v73, v0
	s_waitcnt lgkmcnt(0)
	v_add_f32_e32 v0, v0, v4
	ds_bpermute_b32 v4, v74, v0
	s_waitcnt lgkmcnt(0)
	v_add_f32_e32 v0, v0, v4
	ds_bpermute_b32 v4, v75, v0
	s_waitcnt lgkmcnt(0)
	v_add_f32_e32 v0, v0, v4
	ds_bpermute_b32 v4, v76, v0
	s_waitcnt lgkmcnt(0)
	v_add_f32_e32 v0, v0, v4
	v_fmamk_f32 v0, v0, 0x3a000000, v169
	v_cmp_gt_f32_e32 vcc, s56, v0
	v_mul_f32_e32 v4, 0x4b800000, v0
	s_nop 0
	v_cndmask_b32_e32 v0, v0, v4, vcc
	v_rsq_f32_e32 v0, v0
	s_nop 0
	v_mul_f32_e32 v4, 0x45800000, v0
	v_cndmask_b32_e32 v20, v0, v4, vcc
	v_mov_b32_e32 v21, v20
	v_pk_mul_f32 v[4:5], v[30:31], v[20:21] op_sel_hi:[1,0]
	v_pk_mul_f32 v[8:9], v[78:79], v[20:21] op_sel_hi:[1,0]
	s_nop 1
	v_mov_b64_e32 v[28:29], v[86:87]
	v_mov_b64_e32 v[30:31], v[88:89]
	s_nop 1
	v_mov_b64_e32 v[78:79], v[118:119]
	v_mov_b64_e32 v[80:81], v[120:121]
	s_and_b64 vcc, exec, s[30:31]
	v_pk_fma_f32 v[30:31], v[30:31], v[8:9], v[80:81]
	v_pk_fma_f32 v[28:29], v[28:29], v[4:5], v[78:79]
	v_pk_mul_f32 v[4:5], v[26:27], v[20:21]
	global_store_dwordx4 v[60:61], v[28:31], off
	s_cbranch_vccz .LBB0_902
; __device__ __forceinline__ void phase_ln(KP p, int l) {
;     ...
; #pragma unroll
;         for (int j = 0; j < 8; ++j) { const int c = lane * 4 + 256 * j;
;             const f32x4 y = v[j] * rstd * *(const f32x4*)(lng + c) + *(const f32x4*)(lnb + c);
;             *(f32x4*)(xr + 256 * j) = y;
;             if (l + 1 < DEPTH) { u32x2 wv; wv.x = pk2(y[0], y[1]); wv.y = pk2(y[2], y[3]); *(u32x2*)(xb + (size_t)row * DM + c) = wv; } }
;     }
	s_nop 1
	v_mov_b64_e32 v[78:79], v[90:91]
	v_mov_b64_e32 v[80:81], v[92:93]
	s_nop 1
	v_mov_b64_e32 v[82:83], v[122:123]
	v_mov_b64_e32 v[84:85], v[124:125]
	v_mov_b32_e32 v8, v20
	v_mov_b32_e32 v9, v20
	v_mov_b32_e32 v68, v71
	v_pk_mul_f32 v[8:9], v[68:69], v[8:9]
	s_mov_b64 s[24:25], 0
	v_pk_fma_f32 v[80:81], v[8:9], v[80:81], v[84:85]
	v_pk_fma_f32 v[78:79], v[4:5], v[78:79], v[82:83]
	global_store_dwordx4 v[60:61], v[78:81], off offset:1024
.LBB0_902:
	v_lshlrev_b64 v[8:9], 12, v[34:35]
	v_lshl_add_u64 v[26:27], s[28:29], 0, v[8:9]
	s_andn2_b64 vcc, exec, s[24:25]
	v_lshlrev_b32_e32 v0, 1, v36
	s_cbranch_vccnz .LBB0_904
	v_cvt_pk_bf16_f32 v8, v28, v29
	v_cvt_pk_bf16_f32 v9, v30, v31
	v_lshl_add_u64 v[16:17], v[26:27], 0, v[0:1]
	global_store_dwordx2 v[16:17], v[8:9], off
	v_mov_b32_e32 v8, v20
	v_mov_b32_e32 v9, v20
	v_mov_b32_e32 v68, v71
	v_pk_mul_f32 v[8:9], v[68:69], v[8:9]
	s_nop 1
	v_mov_b64_e32 v[28:29], v[90:91]
	v_mov_b64_e32 v[30:31], v[92:93]
	s_nop 1
	v_mov_b64_e32 v[68:69], v[122:123]
	v_mov_b64_e32 v[70:71], v[124:125]
	v_pk_fma_f32 v[30:31], v[8:9], v[30:31], v[70:71]
	v_pk_fma_f32 v[28:29], v[4:5], v[28:29], v[68:69]
	v_cvt_pk_bf16_f32 v5, v30, v31
	v_cvt_pk_bf16_f32 v4, v28, v29
	global_store_dwordx4 v[60:61], v[28:31], off offset:1024
	global_store_dwordx2 v[16:17], v[4:5], off offset:512
.LBB0_904:
	s_nop 1
	v_mov_b64_e32 v[28:29], v[94:95]
	v_mov_b64_e32 v[30:31], v[96:97]
	s_nop 0
	s_nop 1
	v_mov_b64_e32 v[68:69], v[126:127]
	v_mov_b64_e32 v[70:71], v[128:129]
	v_mov_b32_e32 v8, v20
	v_mov_b32_e32 v9, v20
	v_pk_mul_f32 v[16:17], v[18:19], v[20:21]
	v_pk_mul_f32 v[18:19], v[66:67], v[8:9]
	s_mov_b64 s[24:25], -1
	s_and_b64 vcc, exec, s[30:31]
	v_pk_mul_f32 v[4:5], v[22:23], v[20:21]
	v_pk_fma_f32 v[18:19], v[18:19], v[30:31], v[70:71]
	v_pk_fma_f32 v[16:17], v[16:17], v[28:29], v[68:69]
	global_store_dwordx4 v[60:61], v[16:19], off offset:2048
	s_cbranch_vccz .LBB0_906
	s_nop 1
	v_mov_b64_e32 v[28:29], v[98:99]
	v_mov_b64_e32 v[30:31], v[100:101]
	s_nop 1
	v_mov_b64_e32 v[66:67], v[130:131]
	v_mov_b64_e32 v[68:69], v[132:133]
	v_pk_mul_f32 v[8:9], v[64:65], v[8:9]
	s_mov_b64 s[24:25], 0
	v_pk_fma_f32 v[30:31], v[8:9], v[30:31], v[68:69]
	v_pk_fma_f32 v[28:29], v[4:5], v[28:29], v[66:67]
	global_store_dwordx4 v[60:61], v[28:31], off offset:3072
.LBB0_906:
	s_andn2_b64 vcc, exec, s[24:25]
	s_cbranch_vccnz .LBB0_908
	v_cvt_pk_bf16_f32 v8, v16, v17
	v_cvt_pk_bf16_f32 v9, v18, v19
	v_lshl_add_u64 v[22:23], v[26:27], 0, v[0:1]
	global_store_dwordx2 v[22:23], v[8:9], off offset:1024
	s_nop 1
	v_mov_b64_e32 v[16:17], v[98:99]
	v_mov_b64_e32 v[18:19], v[100:101]
	s_nop 1
	v_mov_b64_e32 v[28:29], v[130:131]
	v_mov_b64_e32 v[30:31], v[132:133]
	v_mov_b32_e32 v8, v20
	v_mov_b32_e32 v9, v20
	v_pk_mul_f32 v[8:9], v[64:65], v[8:9]
	v_pk_fma_f32 v[16:17], v[4:5], v[16:17], v[28:29]
	v_pk_fma_f32 v[18:19], v[8:9], v[18:19], v[30:31]
	v_cvt_pk_bf16_f32 v4, v16, v17
	v_cvt_pk_bf16_f32 v5, v18, v19
	global_store_dwordx4 v[60:61], v[16:19], off offset:3072
	global_store_dwordx2 v[22:23], v[4:5], off offset:1536
.LBB0_908:
	s_nop 1
	v_mov_b64_e32 v[28:29], v[102:103]
	v_mov_b64_e32 v[30:31], v[104:105]
	s_nop 1
	v_mov_b64_e32 v[64:65], v[134:135]
	v_mov_b64_e32 v[66:67], v[136:137]
	v_mov_b32_e32 v16, v20
	v_mov_b32_e32 v17, v20
	s_mov_b64 s[22:23], 0x1400
	v_pk_mul_f32 v[8:9], v[10:11], v[20:21]
	v_pk_mul_f32 v[10:11], v[62:63], v[16:17]
	v_lshl_add_u64 v[18:19], v[60:61], 0, s[10:11]
	v_lshl_add_u64 v[4:5], v[60:61], 0, s[22:23]
	s_mov_b64 s[24:25], -1
	s_and_b64 vcc, exec, s[30:31]
	v_pk_mul_f32 v[14:15], v[14:15], v[20:21]
	v_pk_fma_f32 v[10:11], v[10:11], v[30:31], v[66:67]
	v_pk_fma_f32 v[8:9], v[8:9], v[28:29], v[64:65]
	global_store_dwordx4 v[18:19], v[8:11], off
	s_cbranch_vccz .LBB0_910
	s_nop 1
	v_mov_b64_e32 v[28:29], v[106:107]
	v_mov_b64_e32 v[30:31], v[108:109]
	s_nop 1
	v_mov_b64_e32 v[62:63], v[174:175]
	v_mov_b64_e32 v[64:65], v[176:177]
	v_pk_mul_f32 v[16:17], v[32:33], v[16:17]
	s_mov_b64 s[24:25], 0
	v_pk_fma_f32 v[18:19], v[16:17], v[30:31], v[64:65]
	v_pk_fma_f32 v[16:17], v[14:15], v[28:29], v[62:63]
	global_store_dwordx4 v[4:5], v[16:19], off
.LBB0_910:
	s_andn2_b64 vcc, exec, s[24:25]
	s_cbranch_vccnz .LBB0_912
	v_cvt_pk_bf16_f32 v8, v8, v9
	v_cvt_pk_bf16_f32 v9, v10, v11
	v_lshl_add_u64 v[22:23], v[26:27], 0, v[0:1]
	global_store_dwordx2 v[22:23], v[8:9], off offset:2048
	v_mov_b32_e32 v8, v20
	v_mov_b32_e32 v9, v20
	v_pk_mul_f32 v[28:29], v[32:33], v[8:9]
	s_nop 1
	v_mov_b64_e32 v[8:9], v[106:107]
	v_mov_b64_e32 v[10:11], v[108:109]
	s_nop 1
	v_mov_b64_e32 v[16:17], v[174:175]
	v_mov_b64_e32 v[18:19], v[176:177]
	v_pk_fma_f32 v[10:11], v[28:29], v[10:11], v[18:19]
	v_pk_fma_f32 v[8:9], v[14:15], v[8:9], v[16:17]
	global_store_dwordx4 v[4:5], v[8:11], off
	v_cvt_pk_bf16_f32 v4, v8, v9
	v_cvt_pk_bf16_f32 v5, v10, v11
	global_store_dwordx2 v[22:23], v[4:5], off offset:2560
.LBB0_912:
	s_nop 1
	v_mov_b64_e32 v[14:15], v[110:111]
	v_mov_b64_e32 v[16:17], v[112:113]
	s_nop 1
	v_mov_b64_e32 v[28:29], v[178:179]
	v_mov_b64_e32 v[30:31], v[180:181]
	s_mov_b64 s[22:23], 0x1800
	v_mov_b32_e32 v10, v20
	v_mov_b32_e32 v11, v20
	v_lshl_add_u64 v[18:19], v[60:61], 0, s[22:23]
	s_mov_b64 s[22:23], 0x1c00
	v_pk_mul_f32 v[22:23], v[6:7], v[20:21]
	v_pk_mul_f32 v[6:7], v[2:3], v[20:21]
	v_pk_mul_f32 v[2:3], v[24:25], v[10:11]
	v_lshl_add_u64 v[8:9], v[60:61], 0, s[22:23]
	s_mov_b64 s[24:25], -1
	s_and_b64 vcc, exec, s[30:31]
	v_pk_fma_f32 v[4:5], v[2:3], v[16:17], v[30:31]
	v_pk_fma_f32 v[2:3], v[22:23], v[14:15], v[28:29]
	global_store_dwordx4 v[18:19], v[2:5], off
	s_cbranch_vccz .LBB0_914
	s_nop 1
	v_mov_b64_e32 v[14:15], v[114:115]
	v_mov_b64_e32 v[16:17], v[116:117]
	s_nop 1
	v_mov_b64_e32 v[22:23], v[182:183]
	v_mov_b64_e32 v[24:25], v[184:185]
	v_pk_mul_f32 v[10:11], v[12:13], v[10:11]
	s_mov_b64 s[24:25], 0
	v_pk_fma_f32 v[16:17], v[10:11], v[16:17], v[24:25]
	v_pk_fma_f32 v[14:15], v[6:7], v[14:15], v[22:23]
	global_store_dwordx4 v[8:9], v[14:17], off
.LBB0_914:
	s_andn2_b64 vcc, exec, s[24:25]
	s_cbranch_vccnz .LBB0_899
	v_cvt_pk_bf16_f32 v2, v2, v3
	v_cvt_pk_bf16_f32 v3, v4, v5
	v_lshl_add_u64 v[14:15], v[26:27], 0, v[0:1]
	global_store_dwordx2 v[14:15], v[2:3], off offset:3072
	v_mov_b32_e32 v21, v20
	v_pk_mul_f32 v[16:17], v[12:13], v[20:21]
	s_nop 1
	v_mov_b64_e32 v[2:3], v[114:115]
	v_mov_b64_e32 v[4:5], v[116:117]
	s_nop 1
	v_mov_b64_e32 v[10:11], v[182:183]
	v_mov_b64_e32 v[12:13], v[184:185]
	v_pk_fma_f32 v[4:5], v[16:17], v[4:5], v[12:13]
	v_pk_fma_f32 v[2:3], v[6:7], v[2:3], v[10:11]
	global_store_dwordx4 v[8:9], v[2:5], off
	s_nop 1
	v_cvt_pk_bf16_f32 v2, v2, v3
	v_cvt_pk_bf16_f32 v3, v4, v5
	global_store_dwordx2 v[14:15], v[2:3], off offset:3584
	s_branch .LBB0_899
